# comb25 + attention: the first two V-fragment reads of the P.V block are issued inside the QK^T block (spare registers), ahead of the last four QK MFMAs
# speedup vs baseline: 1.0098x; 1.0010x over previous
; #define LAS __attribute__((address_space(3)))
; __device__ __forceinline__ unsigned cvt_pk(float lo, float hi) { unsigned r; asm volatile("v_cvt_pk_bf16_f32 %0, %1, %2" : "=v"(r) : "v"(lo), "v"(hi)); return r; }
; __device__ __forceinline__ void attn_unit(LAS unsigned char* lds, int b, int h, int q0, int kbeg, int ntiles, const bf16_t* Q, const bf16_t* K, const bf16_t* Vt, bf16_t* cat) {
;     ...
;         const LAS unsigned char* kb = lds + (buf ^ 1) * AK_BYTES + r32 * (KP * 2) + hi * 16;
;         f32x16 pn0, pn1;
; #pragma unroll
;         for (int r = 0; r < 16; ++r) { pn0[r] = 0.f; pn1[r] = 0.f; }
;         float ps = 0.f; u32x4 pw[4];
;         bf16x8 ka = *(const LAS bf16x8*)(kb), kbb = *(const LAS bf16x8*)(kb + 32 * (KP * 2));
; #pragma unroll
;         for (int ds = 0; ds < 12; ++ds) {
;             bf16x8 na = ka, nb = kbb;
;             if (ds < 11) { na = *(const LAS bf16x8*)(kb + (ds + 1) * 32); nb = *(const LAS bf16x8*)(kb + 32 * (KP * 2) + (ds + 1) * 32); }
;             pn0 = __builtin_amdgcn_mfma_f32_32x32x16_bf16(ka, qf[ds], pn0, 0, 0, 0);
;             pn1 = __builtin_amdgcn_mfma_f32_32x32x16_bf16(kbb, qf[ds], pn1, 0, 0, 0);
;             if (ds < 8) {
;                 float e[4];
; #pragma unroll
;                 for (int j = 0; j < 4; ++j) { const float v = ds < 4 ? pc0[4 * ds + j] : pc1[4 * (ds - 4) + j]; e[j] = __builtin_amdgcn_exp2f(v - mrun); }
;                 ps += (e[0] + e[1]) + (e[2] + e[3]);
;                 const unsigned w0 = cvt_pk(e[0], e[1]), w1 = cvt_pk(e[2], e[3]);
;                 if ((ds & 1) == 0) { pw[ds >> 1].x = w0; pw[ds >> 1].y = w1; } else { pw[ds >> 1].z = w0; pw[ds >> 1].w = w1; }
;             }
;             ka = na; kbb = nb;
;             __builtin_amdgcn_sched_barrier(0);
;         }
.LBB0_814:
	s_xor_b32 s6, s5, 1
	v_sub_f32_e32 v82, v82, v230
	v_exp_f32_e32 v197, v82
	v_sub_f32_e32 v82, v84, v230
	v_exp_f32_e32 v201, v82
	v_sub_f32_e32 v82, v85, v230
	v_exp_f32_e32 v233, v82
	v_sub_f32_e32 v82, v86, v230
	v_exp_f32_e32 v196, v82
	v_sub_f32_e32 v82, v87, v230
	s_waitcnt lgkmcnt(0)
	v_mfma_f32_32x32x16_bf16 v[98:113], v[240:243], v[174:177], 0
	v_exp_f32_e32 v198, v82
	v_sub_f32_e32 v82, v88, v230
	v_sub_f32_e32 v83, v83, v230
	v_exp_f32_e32 v200, v82
	v_sub_f32_e32 v82, v89, v230
	v_exp_f32_e32 v199, v83
	v_exp_f32_e32 v232, v82
	s_add_i32 s4, s4, 1
	v_add_f32_e32 v82, v196, v198
	v_add_f32_e32 v83, v197, v199
	v_add_f32_e32 v84, v200, v232
	v_add_f32_e32 v85, v201, v233
	s_waitcnt lgkmcnt(1)
	v_mfma_f32_32x32x16_bf16 v[114:129], v[114:117], v[174:177], 0
	v_add_f32_e64 v234, v82, v84
	v_add_f32_e64 v235, v83, v85
	v_cvt_pk_bf16_f32 v186, v197, v199
	v_cvt_pk_bf16_f32 v187, v201, v233
	v_add_f32_e32 v235, 0, v235
	v_mfma_f32_32x32x16_bf16 v[98:113], v[188:191], v[170:173], v[98:113]
	ds_read_b128 v[82:85], v236 offset:64
	ds_read_b128 v[86:89], v236 offset:12864
	v_add_f32_e32 v197, v234, v235
	v_cvt_pk_bf16_f32 v188, v196, v198
	v_cvt_pk_bf16_f32 v189, v200, v232
	s_waitcnt lgkmcnt(2)
	v_mfma_f32_32x32x16_bf16 v[114:129], v[192:195], v[170:173], v[114:129]
	v_sub_f32_e32 v90, v90, v230
	s_waitcnt lgkmcnt(1)
	v_mfma_f32_32x32x16_bf16 v[98:113], v[82:85], v[166:169], v[98:113]
	v_exp_f32_e32 v190, v90
	v_sub_f32_e32 v90, v91, v230
	v_exp_f32_e32 v192, v90
	v_sub_f32_e32 v90, v92, v230
	v_sub_f32_e32 v82, v93, v230
	v_exp_f32_e32 v191, v90
	v_exp_f32_e32 v193, v82
	ds_read_b128 v[82:85], v236 offset:96
	ds_read_b128 v[90:93], v236 offset:12896
	s_waitcnt lgkmcnt(2)
	v_mfma_f32_32x32x16_bf16 v[114:129], v[86:89], v[166:169], v[114:129]
	v_add_f32_e64 v194, v190, v192
	v_add_f32_e64 v195, v191, v193
	v_add_f32_e64 v198, v194, v194
	v_add_f32_e64 v199, v194, v195
	v_cvt_pk_bf16_f32 v190, v190, v192
	v_cvt_pk_bf16_f32 v191, v191, v193
	v_sub_f32_e32 v86, v94, v230
	s_waitcnt lgkmcnt(1)
	v_mfma_f32_32x32x16_bf16 v[98:113], v[82:85], v[162:165], v[98:113]
	v_exp_f32_e32 v94, v86
	v_sub_f32_e32 v86, v95, v230
	v_exp_f32_e32 v192, v86
	v_sub_f32_e32 v86, v96, v230
	v_sub_f32_e32 v82, v97, v230
	v_exp_f32_e32 v96, v86
	v_exp_f32_e32 v193, v82
	ds_read_b128 v[82:85], v236 offset:128
	ds_read_b128 v[86:89], v236 offset:12928
	v_add_f32_e32 v95, v94, v192
	v_cvt_pk_bf16_f32 v192, v94, v192
	v_add_f32_e32 v97, v96, v193
	s_waitcnt lgkmcnt(2)
	v_mfma_f32_32x32x16_bf16 v[114:129], v[90:93], v[162:165], v[114:129]
	v_cvt_pk_bf16_f32 v193, v96, v193
	v_sub_f32_e32 v66, v66, v230
	v_exp_f32_e32 v94, v66
	v_sub_f32_e32 v66, v67, v230
	v_exp_f32_e32 v96, v66
	v_sub_f32_e32 v66, v68, v230
	v_exp_f32_e32 v198, v66
	s_waitcnt lgkmcnt(1)
	v_mfma_f32_32x32x16_bf16 v[98:113], v[82:85], v[158:161], v[98:113]
	v_sub_f32_e32 v66, v69, v230
	v_exp_f32_e32 v196, v66
	ds_read_b128 v[66:69], v236 offset:160
	ds_read_b128 v[82:85], v236 offset:12960
	v_add_f32_e32 v90, v94, v96
	v_add_f32_e32 v91, v95, v97
	v_cvt_pk_bf16_f32 v194, v94, v96
	v_add_f32_e32 v92, v198, v196
	v_add_f32_e32 v93, v199, v197
	v_cvt_pk_bf16_f32 v195, v198, v196
	s_waitcnt lgkmcnt(2)
	v_mfma_f32_32x32x16_bf16 v[114:129], v[86:89], v[158:161], v[114:129]
	v_add_f32_e64 v90, v90, v92
	v_add_f32_e64 v91, v91, v93
	v_add_f32_e64 v86, v90, v90
	v_add_f32_e64 v87, v90, v91
	v_sub_f32_e32 v70, v70, v230
	v_exp_f32_e32 v88, v70
	v_sub_f32_e32 v70, v71, v230
	s_waitcnt lgkmcnt(1)
	v_mfma_f32_32x32x16_bf16 v[98:113], v[66:69], v[154:157], v[98:113]
	v_exp_f32_e32 v90, v70
	v_sub_f32_e32 v70, v72, v230
	v_sub_f32_e32 v66, v73, v230
	v_exp_f32_e32 v89, v70
	v_exp_f32_e32 v91, v66
	ds_read_b128 v[66:69], v236 offset:192
	ds_read_b128 v[70:73], v236 offset:12992
	v_cvt_pk_bf16_f32 v196, v88, v90
	s_waitcnt lgkmcnt(2)
	v_mfma_f32_32x32x16_bf16 v[114:129], v[82:85], v[154:157], v[114:129]
	v_add_f32_e64 v92, v88, v90
	v_add_f32_e64 v93, v89, v91
	v_cvt_pk_bf16_f32 v197, v89, v91
	v_add_f32_e32 v93, v92, v93
	v_add_f32_e32 v92, v92, v92
	v_sub_f32_e32 v74, v74, v230
	s_waitcnt lgkmcnt(1)
	v_mfma_f32_32x32x16_bf16 v[98:113], v[66:69], v[150:153], v[98:113]
	v_exp_f32_e32 v82, v74
	v_sub_f32_e32 v74, v75, v230
	v_exp_f32_e32 v84, v74
	v_sub_f32_e32 v74, v76, v230
	v_sub_f32_e32 v66, v77, v230
	v_exp_f32_e32 v86, v74
	v_exp_f32_e32 v88, v66
	ds_read_b128 v[66:69], v236 offset:224
	ds_read_b128 v[74:77], v236 offset:13024
	v_add_f32_e32 v83, v82, v84
	v_cvt_pk_bf16_f32 v198, v82, v84
	v_add_f32_e32 v85, v86, v88
	s_waitcnt lgkmcnt(2)
	v_mfma_f32_32x32x16_bf16 v[114:129], v[70:73], v[150:153], v[114:129]
	v_cvt_pk_bf16_f32 v199, v86, v88
	v_sub_f32_e32 v70, v78, v230
	v_exp_f32_e32 v82, v70
	v_sub_f32_e32 v70, v79, v230
	s_waitcnt lgkmcnt(1)
	v_mfma_f32_32x32x16_bf16 v[98:113], v[66:69], v[146:149], v[98:113]
	v_exp_f32_e32 v84, v70
	v_sub_f32_e32 v70, v80, v230
	v_sub_f32_e32 v66, v81, v230
	v_exp_f32_e32 v92, v70
	v_exp_f32_e32 v86, v66
	ds_read_b128 v[66:69], v236 offset:256
	ds_read_b128 v[70:73], v236 offset:13056
	v_add_f32_e32 v78, v82, v84
	v_add_f32_e32 v79, v83, v85
	s_waitcnt lgkmcnt(2)
; #define LAS __attribute__((address_space(3)))
; __device__ __forceinline__ unsigned cvt_pk(float lo, float hi) { unsigned r; asm volatile("v_cvt_pk_bf16_f32 %0, %1, %2" : "=v"(r) : "v"(lo), "v"(hi)); return r; }
; __device__ __forceinline__ void attn_unit(LAS unsigned char* lds, int b, int h, int q0, int kbeg, int ntiles, const bf16_t* Q, const bf16_t* K, const bf16_t* Vt, bf16_t* cat) {
;     ...
;         for (int ds = 0; ds < 12; ++ds) {
;             bf16x8 na = ka, nb = kbb;
;             if (ds < 11) { na = *(const LAS bf16x8*)(kb + (ds + 1) * 32); nb = *(const LAS bf16x8*)(kb + 32 * (KP * 2) + (ds + 1) * 32); }
;             pn0 = __builtin_amdgcn_mfma_f32_32x32x16_bf16(ka, qf[ds], pn0, 0, 0, 0);
;             pn1 = __builtin_amdgcn_mfma_f32_32x32x16_bf16(kbb, qf[ds], pn1, 0, 0, 0);
;             if (ds < 8) {
;                 float e[4];
; #pragma unroll
;                 for (int j = 0; j < 4; ++j) { const float v = ds < 4 ? pc0[4 * ds + j] : pc1[4 * (ds - 4) + j]; e[j] = __builtin_amdgcn_exp2f(v - mrun); }
;                 ps += (e[0] + e[1]) + (e[2] + e[3]);
;                 const unsigned w0 = cvt_pk(e[0], e[1]), w1 = cvt_pk(e[2], e[3]);
;                 if ((ds & 1) == 0) { pw[ds >> 1].x = w0; pw[ds >> 1].y = w1; } else { pw[ds >> 1].z = w0; pw[ds >> 1].w = w1; }
;             }
;             ka = na; kbb = nb;
;             __builtin_amdgcn_sched_barrier(0);
;         }
;         lrun += ps;
;         const LAS unsigned char* vb = lds + 2 * AK_BYTES + buf * AV_BYTES + r32 * AV_PITCH + hi * 8;
; #pragma unroll
;         for (int d = 0; d < 4; ++d)
; #pragma unroll
;             for (int ks = 0; ks < 4; ++ks) {
;                 const s16x4 lo = *(const LAS s16x4*)(vb + d * 32 * AV_PITCH + ks * 32), hh = *(const LAS s16x4*)(vb + d * 32 * AV_PITCH + ks * 32 + 16);
;                 const bf16x8 vf = (bf16x8){lo[0], lo[1], lo[2], lo[3], hh[0], hh[1], hh[2], hh[3]};
;                 o[d] = __builtin_amdgcn_mfma_f32_32x32x16_bf16(vf, __builtin_bit_cast(bf16x8, pw[ks]), o[d], 0, 0, 0);
;             }
;         { float mx = fmaxf(pn0[0], pn1[0]);
; #pragma unroll
;           for (int r = 1; r < 16; ++r) mx = fmaxf(mx, fmaxf(pn0[r], pn1[r]));
;           mxc = fmaxf(mx, __shfl_xor(mx, 32)); }
;         if (kt + 1 < ntiles) ASTOREV(buf ^ 1);
;         asm volatile("s_waitcnt vmcnt(0)" ::: "memory");
;         __syncthreads();
	v_mfma_f32_32x32x16_bf16 v[114:129], v[74:77], v[146:149], v[114:129]
	v_add_f32_e64 v80, v92, v86
	v_add_f32_e64 v81, v93, v87
	v_cvt_pk_bf16_f32 v200, v82, v84
	v_cvt_pk_bf16_f32 v201, v92, v86
	v_add_f32_e64 v78, v78, v80
	v_add_f32_e64 v79, v79, v81
	v_add_f32_e32 v237, v78, v79
	s_waitcnt lgkmcnt(1)
	v_mfma_f32_32x32x16_bf16 v[98:113], v[66:69], v[142:145], v[98:113]
	ds_read_b128 v[66:69], v236 offset:288
	ds_read_b128 v[74:77], v236 offset:13088
	s_waitcnt lgkmcnt(2)
	v_mfma_f32_32x32x16_bf16 v[114:129], v[70:73], v[142:145], v[114:129]
	s_waitcnt lgkmcnt(1)
	v_mfma_f32_32x32x16_bf16 v[98:113], v[66:69], v[138:141], v[98:113]
	s_mul_i32 s98, s5, 0x4400
	v_add_u32_e32 v249, s98, v229
	v_add_u32_e32 v250, 0xc800, v249
	v_add_u32_e32 v251, 0xd800, v249
	ds_read2_b64 v[240:243], v250 offset1:2
	ds_read2_b64 v[244:247], v251 offset0:32 offset1:34
	ds_read_b128 v[66:69], v236 offset:320
	ds_read_b128 v[70:73], v236 offset:13120
	s_waitcnt lgkmcnt(4)
	v_mfma_f32_32x32x16_bf16 v[114:129], v[74:77], v[138:141], v[114:129]
	s_waitcnt lgkmcnt(1)
	v_mfma_f32_32x32x16_bf16 v[98:113], v[66:69], v[134:137], v[98:113]
	ds_read_b128 v[66:69], v236 offset:352
	ds_read_b128 v[232:235], v236 offset:13152
	s_waitcnt lgkmcnt(2)
	v_mfma_f32_32x32x16_bf16 v[114:129], v[70:73], v[134:137], v[114:129]
	s_waitcnt lgkmcnt(1)
	v_mfma_f32_32x32x16_bf16 v[82:97], v[66:69], v[130:133], v[98:113]
	s_waitcnt lgkmcnt(0)
	v_mfma_f32_32x32x16_bf16 v[66:81], v[232:235], v[130:133], v[114:129]
	s_mulk_i32 s5, 0x4400
	v_add_u32_e32 v232, s5, v229
	v_add_u32_e32 v250, 0xc800, v232
	v_add_u32_e32 v251, 0xd800, v232
	v_add_u32_e32 v252, 0xe800, v232
	v_add_u32_e32 v253, 0xf800, v232
	s_mulk_i32 s6, 0x4400
	ds_read2_b64 v[106:109], v252 offset0:64 offset1:66
	ds_read2_b64 v[110:113], v253 offset0:96 offset1:98
	ds_read2_b64 v[114:117], v250 offset0:4 offset1:6
	ds_read2_b64 v[118:121], v251 offset0:36 offset1:38
	ds_read2_b64 v[122:125], v252 offset0:68 offset1:70
	ds_read2_b64 v[126:129], v253 offset0:100 offset1:102
	v_add_f32_e32 v202, v202, v237
	v_max3_f32 v254, v82, v66, v83
	v_max3_f32 v254, v254, v67, v84
	v_max3_f32 v254, v254, v68, v85
	v_max3_f32 v254, v254, v69, v86
	s_waitcnt lgkmcnt(7)
	v_mfma_f32_32x32x16_bf16 v[50:65], v[240:243], v[186:189], v[50:65]
	ds_read2_b64 v[98:101], v250 offset0:8 offset1:10
	v_max3_f32 v254, v254, v70, v87
	v_max3_f32 v254, v254, v71, v88
	s_waitcnt lgkmcnt(7)
	v_mfma_f32_32x32x16_bf16 v[34:49], v[244:247], v[186:189], v[34:49]
	ds_read2_b64 v[102:105], v251 offset0:40 offset1:42
	v_max3_f32 v254, v254, v72, v89
	v_max3_f32 v254, v254, v73, v90
	s_waitcnt lgkmcnt(7)
	v_mfma_f32_32x32x16_bf16 v[18:33], v[106:109], v[186:189], v[18:33]
	ds_read2_b64 v[106:109], v252 offset0:72 offset1:74
	v_max3_f32 v254, v254, v74, v91
	v_max3_f32 v254, v254, v75, v92
	s_waitcnt lgkmcnt(7)
	v_mfma_f32_32x32x16_bf16 v[2:17], v[110:113], v[186:189], v[2:17]
	ds_read2_b64 v[110:113], v253 offset0:104 offset1:106
	v_max3_f32 v254, v254, v76, v93
	v_max3_f32 v254, v254, v77, v94
	s_waitcnt lgkmcnt(7)
	v_mfma_f32_32x32x16_bf16 v[50:65], v[114:117], v[190:193], v[50:65]
	ds_read2_b64 v[114:117], v250 offset0:12 offset1:14
	v_max3_f32 v254, v254, v78, v95
	v_max3_f32 v254, v254, v79, v96
	s_waitcnt lgkmcnt(7)
	v_mfma_f32_32x32x16_bf16 v[34:49], v[118:121], v[190:193], v[34:49]
	ds_read2_b64 v[118:121], v251 offset0:44 offset1:46
	v_max3_f32 v254, v254, v80, v97
	v_max_f32_e32 v254, v254, v81
	s_waitcnt lgkmcnt(7)
	v_mfma_f32_32x32x16_bf16 v[18:33], v[122:125], v[190:193], v[18:33]
	ds_read2_b64 v[122:125], v252 offset0:76 offset1:78
	v_lshl_add_u64 v[212:213], v[212:213], 0, s[60:61]
	v_lshl_add_u64 v[214:215], v[214:215], 0, s[60:61]
	s_waitcnt lgkmcnt(7)
	v_mfma_f32_32x32x16_bf16 v[2:17], v[126:129], v[190:193], v[2:17]
	ds_read2_b64 v[126:129], v253 offset0:108 offset1:110
	v_lshl_add_u64 v[216:217], v[216:217], 0, s[60:61]
	v_lshl_add_u64 v[218:219], v[218:219], 0, s[60:61]
	v_lshl_add_u64 v[220:221], v[220:221], 0, s[66:67]
	ds_bpermute_b32 v255, v207, v254
	s_waitcnt lgkmcnt(8)
	v_mfma_f32_32x32x16_bf16 v[50:65], v[98:101], v[194:197], v[50:65]
	s_waitcnt lgkmcnt(7)
	v_mfma_f32_32x32x16_bf16 v[34:49], v[102:105], v[194:197], v[34:49]
	s_waitcnt lgkmcnt(6)
	v_mfma_f32_32x32x16_bf16 v[18:33], v[106:109], v[194:197], v[18:33]
	s_waitcnt lgkmcnt(5)
	v_mfma_f32_32x32x16_bf16 v[2:17], v[110:113], v[194:197], v[2:17]
	s_waitcnt lgkmcnt(0)
	v_max_f32_e32 v255, v255, v255
	v_max_f32_e32 v98, v254, v255
	v_add_u32_e32 v255, s6, v231
	v_add_u32_e32 v238, 0xc800, v255
	v_add_u32_e32 v255, 0xea00, v255
	s_cmp_lg_u32 s4, 34
	s_waitcnt vmcnt(0)
	ds_write2_b64 v238, v[178:179], v[180:181] offset1:1
	ds_write2_b64 v255, v[182:183], v[184:185] offset1:1
	s_waitcnt vmcnt(0)
	s_waitcnt lgkmcnt(0)
	s_barrier
	v_mfma_f32_32x32x16_bf16 v[50:65], v[114:117], v[198:201], v[50:65]
	v_mfma_f32_32x32x16_bf16 v[34:49], v[118:121], v[198:201], v[34:49]
	v_mfma_f32_32x32x16_bf16 v[18:33], v[122:125], v[198:201], v[18:33]
	v_mfma_f32_32x32x16_bf16 v[2:17], v[126:129], v[198:201], v[2:17]
	s_cbranch_scc0 .LBB0_819

; #define LAS __attribute__((address_space(3)))
; __device__ __forceinline__ unsigned cvt_pk(float lo, float hi) { unsigned r; asm volatile("v_cvt_pk_bf16_f32 %0, %1, %2" : "=v"(r) : "v"(lo), "v"(hi)); return r; }
; __device__ __forceinline__ void attn_unit(LAS unsigned char* lds, int b, int h, int q0, int kbeg, int ntiles, const bf16_t* Q, const bf16_t* K, const bf16_t* Vt, bf16_t* cat) {
;     ...
;         const LAS unsigned char* kb = lds + (buf ^ 1) * AK_BYTES + r32 * (KP * 2) + hi * 16;
;         f32x16 pn0, pn1;
; #pragma unroll
;         for (int r = 0; r < 16; ++r) { pn0[r] = 0.f; pn1[r] = 0.f; }
;         float ps = 0.f; u32x4 pw[4];
;         bf16x8 ka = *(const LAS bf16x8*)(kb), kbb = *(const LAS bf16x8*)(kb + 32 * (KP * 2));
; #pragma unroll
;         for (int ds = 0; ds < 12; ++ds) {
;             bf16x8 na = ka, nb = kbb;
;             if (ds < 11) { na = *(const LAS bf16x8*)(kb + (ds + 1) * 32); nb = *(const LAS bf16x8*)(kb + 32 * (KP * 2) + (ds + 1) * 32); }
;             pn0 = __builtin_amdgcn_mfma_f32_32x32x16_bf16(ka, qf[ds], pn0, 0, 0, 0);
;             pn1 = __builtin_amdgcn_mfma_f32_32x32x16_bf16(kbb, qf[ds], pn1, 0, 0, 0);
;             if (ds < 8) {
;                 float e[4];
; #pragma unroll
;                 for (int j = 0; j < 4; ++j) { const float v = ds < 4 ? pc0[4 * ds + j] : pc1[4 * (ds - 4) + j]; e[j] = __builtin_amdgcn_exp2f(v - mrun); }
;                 ps += (e[0] + e[1]) + (e[2] + e[3]);
;                 const unsigned w0 = cvt_pk(e[0], e[1]), w1 = cvt_pk(e[2], e[3]);
;                 if ((ds & 1) == 0) { pw[ds >> 1].x = w0; pw[ds >> 1].y = w1; } else { pw[ds >> 1].z = w0; pw[ds >> 1].w = w1; }
;             }
;             ka = na; kbb = nb;
;             __builtin_amdgcn_sched_barrier(0);
;         }
.LBB0_1840:
	s_xor_b32 s6, s5, 1
	v_sub_f32_e32 v82, v82, v231
	v_exp_f32_e32 v197, v82
	v_sub_f32_e32 v82, v84, v231
	v_exp_f32_e32 v201, v82
	v_sub_f32_e32 v82, v85, v231
	v_exp_f32_e32 v235, v82
	v_sub_f32_e32 v82, v86, v231
	v_exp_f32_e32 v196, v82
	v_sub_f32_e32 v82, v87, v231
	s_waitcnt lgkmcnt(0)
	v_mfma_f32_32x32x16_bf16 v[98:113], v[240:243], v[174:177], 0
	v_exp_f32_e32 v198, v82
	v_sub_f32_e32 v82, v88, v231
	v_sub_f32_e32 v83, v83, v231
	v_exp_f32_e32 v200, v82
	v_sub_f32_e32 v82, v89, v231
	v_exp_f32_e32 v199, v83
	v_exp_f32_e32 v234, v82
	s_add_i32 s4, s4, 1
	v_add_f32_e32 v82, v196, v198
	v_add_f32_e32 v83, v197, v199
	v_add_f32_e32 v84, v200, v234
	v_add_f32_e32 v85, v201, v235
	s_waitcnt lgkmcnt(1)
	v_mfma_f32_32x32x16_bf16 v[114:129], v[114:117], v[174:177], 0
	v_add_f32_e64 v236, v82, v84
	v_add_f32_e64 v237, v83, v85
	v_cvt_pk_bf16_f32 v186, v197, v199
	v_cvt_pk_bf16_f32 v187, v201, v235
	v_add_f32_e32 v237, 0, v237
	v_mfma_f32_32x32x16_bf16 v[98:113], v[188:191], v[170:173], v[98:113]
	ds_read_b128 v[82:85], v233 offset:64
	ds_read_b128 v[86:89], v233 offset:12864
	v_add_f32_e32 v197, v236, v237
	v_cvt_pk_bf16_f32 v188, v196, v198
	v_cvt_pk_bf16_f32 v189, v200, v234
	s_waitcnt lgkmcnt(2)
	v_mfma_f32_32x32x16_bf16 v[114:129], v[192:195], v[170:173], v[114:129]
	v_sub_f32_e32 v90, v90, v231
	s_waitcnt lgkmcnt(1)
	v_mfma_f32_32x32x16_bf16 v[98:113], v[82:85], v[166:169], v[98:113]
	v_exp_f32_e32 v190, v90
	v_sub_f32_e32 v90, v91, v231
	v_exp_f32_e32 v192, v90
	v_sub_f32_e32 v90, v92, v231
	v_sub_f32_e32 v82, v93, v231
	v_exp_f32_e32 v191, v90
	v_exp_f32_e32 v193, v82
	ds_read_b128 v[82:85], v233 offset:96
	ds_read_b128 v[90:93], v233 offset:12896
	s_waitcnt lgkmcnt(2)
	v_mfma_f32_32x32x16_bf16 v[114:129], v[86:89], v[166:169], v[114:129]
	v_add_f32_e64 v194, v190, v192
	v_add_f32_e64 v195, v191, v193
	v_add_f32_e64 v198, v194, v194
	v_add_f32_e64 v199, v194, v195
	v_cvt_pk_bf16_f32 v190, v190, v192
	v_cvt_pk_bf16_f32 v191, v191, v193
	v_sub_f32_e32 v86, v94, v231
	s_waitcnt lgkmcnt(1)
	v_mfma_f32_32x32x16_bf16 v[98:113], v[82:85], v[162:165], v[98:113]
	v_exp_f32_e32 v94, v86
	v_sub_f32_e32 v86, v95, v231
	v_exp_f32_e32 v192, v86
	v_sub_f32_e32 v86, v96, v231
	v_sub_f32_e32 v82, v97, v231
	v_exp_f32_e32 v96, v86
	v_exp_f32_e32 v193, v82
	ds_read_b128 v[82:85], v233 offset:128
	ds_read_b128 v[86:89], v233 offset:12928
	v_add_f32_e32 v95, v94, v192
	v_cvt_pk_bf16_f32 v192, v94, v192
	v_add_f32_e32 v97, v96, v193
	s_waitcnt lgkmcnt(2)
	v_mfma_f32_32x32x16_bf16 v[114:129], v[90:93], v[162:165], v[114:129]
	v_cvt_pk_bf16_f32 v193, v96, v193
	v_sub_f32_e32 v66, v66, v231
	v_exp_f32_e32 v94, v66
	v_sub_f32_e32 v66, v67, v231
	v_exp_f32_e32 v96, v66
	v_sub_f32_e32 v66, v68, v231
	v_exp_f32_e32 v198, v66
	s_waitcnt lgkmcnt(1)
	v_mfma_f32_32x32x16_bf16 v[98:113], v[82:85], v[158:161], v[98:113]
	v_sub_f32_e32 v66, v69, v231
	v_exp_f32_e32 v196, v66
	ds_read_b128 v[66:69], v233 offset:160
	ds_read_b128 v[82:85], v233 offset:12960
	v_add_f32_e32 v90, v94, v96
	v_add_f32_e32 v91, v95, v97
	v_cvt_pk_bf16_f32 v194, v94, v96
	v_add_f32_e32 v92, v198, v196
	v_add_f32_e32 v93, v199, v197
	v_cvt_pk_bf16_f32 v195, v198, v196
	s_waitcnt lgkmcnt(2)
	v_mfma_f32_32x32x16_bf16 v[114:129], v[86:89], v[158:161], v[114:129]
	v_add_f32_e64 v90, v90, v92
	v_add_f32_e64 v91, v91, v93
	v_add_f32_e64 v86, v90, v90
	v_add_f32_e64 v87, v90, v91
	v_sub_f32_e32 v70, v70, v231
	v_exp_f32_e32 v88, v70
	v_sub_f32_e32 v70, v71, v231
	s_waitcnt lgkmcnt(1)
	v_mfma_f32_32x32x16_bf16 v[98:113], v[66:69], v[154:157], v[98:113]
	v_exp_f32_e32 v90, v70
	v_sub_f32_e32 v70, v72, v231
	v_sub_f32_e32 v66, v73, v231
	v_exp_f32_e32 v89, v70
	v_exp_f32_e32 v91, v66
	ds_read_b128 v[66:69], v233 offset:192
	ds_read_b128 v[70:73], v233 offset:12992
	v_cvt_pk_bf16_f32 v196, v88, v90
	s_waitcnt lgkmcnt(2)
	v_mfma_f32_32x32x16_bf16 v[114:129], v[82:85], v[154:157], v[114:129]
	v_add_f32_e64 v92, v88, v90
	v_add_f32_e64 v93, v89, v91
	v_cvt_pk_bf16_f32 v197, v89, v91
	v_add_f32_e32 v93, v92, v93
	v_add_f32_e32 v92, v92, v92
	v_sub_f32_e32 v74, v74, v231
	s_waitcnt lgkmcnt(1)
	v_mfma_f32_32x32x16_bf16 v[98:113], v[66:69], v[150:153], v[98:113]
	v_exp_f32_e32 v82, v74
	v_sub_f32_e32 v74, v75, v231
	v_exp_f32_e32 v84, v74
	v_sub_f32_e32 v74, v76, v231
	v_sub_f32_e32 v66, v77, v231
	v_exp_f32_e32 v86, v74
	v_exp_f32_e32 v88, v66
	ds_read_b128 v[66:69], v233 offset:224
	ds_read_b128 v[74:77], v233 offset:13024
	v_add_f32_e32 v83, v82, v84
	v_cvt_pk_bf16_f32 v198, v82, v84
	v_add_f32_e32 v85, v86, v88
	s_waitcnt lgkmcnt(2)
	v_mfma_f32_32x32x16_bf16 v[114:129], v[70:73], v[150:153], v[114:129]
	v_cvt_pk_bf16_f32 v199, v86, v88
	v_sub_f32_e32 v70, v78, v231
	v_exp_f32_e32 v82, v70
	v_sub_f32_e32 v70, v79, v231
	s_waitcnt lgkmcnt(1)
	v_mfma_f32_32x32x16_bf16 v[98:113], v[66:69], v[146:149], v[98:113]
	v_exp_f32_e32 v84, v70
	v_sub_f32_e32 v70, v80, v231
	v_sub_f32_e32 v66, v81, v231
	v_exp_f32_e32 v92, v70
	v_exp_f32_e32 v86, v66
	ds_read_b128 v[66:69], v233 offset:256
	ds_read_b128 v[70:73], v233 offset:13056
	v_add_f32_e32 v78, v82, v84
	v_add_f32_e32 v79, v83, v85
	s_waitcnt lgkmcnt(2)
; #define LAS __attribute__((address_space(3)))
; __device__ __forceinline__ unsigned cvt_pk(float lo, float hi) { unsigned r; asm volatile("v_cvt_pk_bf16_f32 %0, %1, %2" : "=v"(r) : "v"(lo), "v"(hi)); return r; }
; __device__ __forceinline__ void attn_unit(LAS unsigned char* lds, int b, int h, int q0, int kbeg, int ntiles, const bf16_t* Q, const bf16_t* K, const bf16_t* Vt, bf16_t* cat) {
;     ...
;         for (int ds = 0; ds < 12; ++ds) {
;             bf16x8 na = ka, nb = kbb;
;             if (ds < 11) { na = *(const LAS bf16x8*)(kb + (ds + 1) * 32); nb = *(const LAS bf16x8*)(kb + 32 * (KP * 2) + (ds + 1) * 32); }
;             pn0 = __builtin_amdgcn_mfma_f32_32x32x16_bf16(ka, qf[ds], pn0, 0, 0, 0);
;             pn1 = __builtin_amdgcn_mfma_f32_32x32x16_bf16(kbb, qf[ds], pn1, 0, 0, 0);
;             if (ds < 8) {
;                 float e[4];
; #pragma unroll
;                 for (int j = 0; j < 4; ++j) { const float v = ds < 4 ? pc0[4 * ds + j] : pc1[4 * (ds - 4) + j]; e[j] = __builtin_amdgcn_exp2f(v - mrun); }
;                 ps += (e[0] + e[1]) + (e[2] + e[3]);
;                 const unsigned w0 = cvt_pk(e[0], e[1]), w1 = cvt_pk(e[2], e[3]);
;                 if ((ds & 1) == 0) { pw[ds >> 1].x = w0; pw[ds >> 1].y = w1; } else { pw[ds >> 1].z = w0; pw[ds >> 1].w = w1; }
;             }
;             ka = na; kbb = nb;
;             __builtin_amdgcn_sched_barrier(0);
;         }
;         lrun += ps;
;         const LAS unsigned char* vb = lds + 2 * AK_BYTES + buf * AV_BYTES + r32 * AV_PITCH + hi * 8;
; #pragma unroll
;         for (int d = 0; d < 4; ++d)
; #pragma unroll
;             for (int ks = 0; ks < 4; ++ks) {
;                 const s16x4 lo = *(const LAS s16x4*)(vb + d * 32 * AV_PITCH + ks * 32), hh = *(const LAS s16x4*)(vb + d * 32 * AV_PITCH + ks * 32 + 16);
;                 const bf16x8 vf = (bf16x8){lo[0], lo[1], lo[2], lo[3], hh[0], hh[1], hh[2], hh[3]};
;                 o[d] = __builtin_amdgcn_mfma_f32_32x32x16_bf16(vf, __builtin_bit_cast(bf16x8, pw[ks]), o[d], 0, 0, 0);
;             }
;         { float mx = fmaxf(pn0[0], pn1[0]);
; #pragma unroll
;           for (int r = 1; r < 16; ++r) mx = fmaxf(mx, fmaxf(pn0[r], pn1[r]));
;           mxc = fmaxf(mx, __shfl_xor(mx, 32)); }
;         if (kt + 1 < ntiles) ASTOREV(buf ^ 1);
;         asm volatile("s_waitcnt vmcnt(0)" ::: "memory");
;         __syncthreads();
	v_mfma_f32_32x32x16_bf16 v[114:129], v[74:77], v[146:149], v[114:129]
	v_add_f32_e64 v80, v92, v86
	v_add_f32_e64 v81, v93, v87
	v_cvt_pk_bf16_f32 v200, v82, v84
	v_cvt_pk_bf16_f32 v201, v92, v86
	v_add_f32_e64 v78, v78, v80
	v_add_f32_e64 v79, v79, v81
	v_add_f32_e32 v238, v78, v79
	s_waitcnt lgkmcnt(1)
	v_mfma_f32_32x32x16_bf16 v[98:113], v[66:69], v[142:145], v[98:113]
	ds_read_b128 v[66:69], v233 offset:288
	ds_read_b128 v[74:77], v233 offset:13088
	s_waitcnt lgkmcnt(2)
	v_mfma_f32_32x32x16_bf16 v[114:129], v[70:73], v[142:145], v[114:129]
	s_waitcnt lgkmcnt(1)
	v_mfma_f32_32x32x16_bf16 v[98:113], v[66:69], v[138:141], v[98:113]
	s_mul_i32 s98, s5, 0x4400
	v_add_u32_e32 v249, s98, v230
	v_add_u32_e32 v250, 0xc800, v249
	v_add_u32_e32 v251, 0xd800, v249
	ds_read2_b64 v[240:243], v250 offset1:2
	ds_read2_b64 v[244:247], v251 offset0:32 offset1:34
	ds_read_b128 v[66:69], v233 offset:320
	ds_read_b128 v[70:73], v233 offset:13120
	s_waitcnt lgkmcnt(4)
	v_mfma_f32_32x32x16_bf16 v[114:129], v[74:77], v[138:141], v[114:129]
	s_waitcnt lgkmcnt(1)
	v_mfma_f32_32x32x16_bf16 v[98:113], v[66:69], v[134:137], v[98:113]
	ds_read_b128 v[66:69], v233 offset:352
	ds_read_b128 v[234:237], v233 offset:13152
	s_waitcnt lgkmcnt(2)
	v_mfma_f32_32x32x16_bf16 v[114:129], v[70:73], v[134:137], v[114:129]
	s_waitcnt lgkmcnt(1)
	v_mfma_f32_32x32x16_bf16 v[82:97], v[66:69], v[130:133], v[98:113]
	s_waitcnt lgkmcnt(0)
	v_mfma_f32_32x32x16_bf16 v[66:81], v[234:237], v[130:133], v[114:129]
	s_mulk_i32 s5, 0x4400
	v_add_u32_e32 v233, s5, v230
	v_add_u32_e32 v250, 0xc800, v233
	v_add_u32_e32 v251, 0xd800, v233
	v_add_u32_e32 v252, 0xe800, v233
	v_add_u32_e32 v253, 0xf800, v233
	s_mulk_i32 s6, 0x4400
	ds_read2_b64 v[106:109], v252 offset0:64 offset1:66
	ds_read2_b64 v[110:113], v253 offset0:96 offset1:98
	ds_read2_b64 v[114:117], v250 offset0:4 offset1:6
	ds_read2_b64 v[118:121], v251 offset0:36 offset1:38
	ds_read2_b64 v[122:125], v252 offset0:68 offset1:70
	ds_read2_b64 v[126:129], v253 offset0:100 offset1:102
	v_add_f32_e32 v202, v202, v238
	v_max3_f32 v254, v82, v66, v83
	v_max3_f32 v254, v254, v67, v84
	v_max3_f32 v254, v254, v68, v85
	v_max3_f32 v254, v254, v69, v86
	s_waitcnt lgkmcnt(7)
	v_mfma_f32_32x32x16_bf16 v[50:65], v[240:243], v[186:189], v[50:65]
	ds_read2_b64 v[98:101], v250 offset0:8 offset1:10
	v_max3_f32 v254, v254, v70, v87
	v_max3_f32 v254, v254, v71, v88
	s_waitcnt lgkmcnt(7)
	v_mfma_f32_32x32x16_bf16 v[34:49], v[244:247], v[186:189], v[34:49]
	ds_read2_b64 v[102:105], v251 offset0:40 offset1:42
	v_max3_f32 v254, v254, v72, v89
	v_max3_f32 v254, v254, v73, v90
	s_waitcnt lgkmcnt(7)
	v_mfma_f32_32x32x16_bf16 v[18:33], v[106:109], v[186:189], v[18:33]
	ds_read2_b64 v[106:109], v252 offset0:72 offset1:74
	v_max3_f32 v254, v254, v74, v91
	v_max3_f32 v254, v254, v75, v92
	s_waitcnt lgkmcnt(7)
	v_mfma_f32_32x32x16_bf16 v[2:17], v[110:113], v[186:189], v[2:17]
	ds_read2_b64 v[110:113], v253 offset0:104 offset1:106
	v_max3_f32 v254, v254, v76, v93
	v_max3_f32 v254, v254, v77, v94
	s_waitcnt lgkmcnt(7)
	v_mfma_f32_32x32x16_bf16 v[50:65], v[114:117], v[190:193], v[50:65]
	ds_read2_b64 v[114:117], v250 offset0:12 offset1:14
	v_max3_f32 v254, v254, v78, v95
	v_max3_f32 v254, v254, v79, v96
	s_waitcnt lgkmcnt(7)
	v_mfma_f32_32x32x16_bf16 v[34:49], v[118:121], v[190:193], v[34:49]
	ds_read2_b64 v[118:121], v251 offset0:44 offset1:46
	v_max3_f32 v254, v254, v80, v97
	v_max_f32_e32 v254, v254, v81
	s_waitcnt lgkmcnt(7)
	v_mfma_f32_32x32x16_bf16 v[18:33], v[122:125], v[190:193], v[18:33]
	ds_read2_b64 v[122:125], v252 offset0:76 offset1:78
	v_lshl_add_u64 v[214:215], v[214:215], 0, s[38:39]
	v_lshl_add_u64 v[216:217], v[216:217], 0, s[38:39]
	s_waitcnt lgkmcnt(7)
	v_mfma_f32_32x32x16_bf16 v[2:17], v[126:129], v[190:193], v[2:17]
	ds_read2_b64 v[126:129], v253 offset0:108 offset1:110
	v_lshl_add_u64 v[218:219], v[218:219], 0, s[38:39]
	v_lshl_add_u64 v[220:221], v[220:221], 0, s[38:39]
	v_lshl_add_u64 v[222:223], v[222:223], 0, s[40:41]
	ds_bpermute_b32 v255, v209, v254
	s_waitcnt lgkmcnt(8)
	v_mfma_f32_32x32x16_bf16 v[50:65], v[98:101], v[194:197], v[50:65]
	s_waitcnt lgkmcnt(7)
	v_mfma_f32_32x32x16_bf16 v[34:49], v[102:105], v[194:197], v[34:49]
	s_waitcnt lgkmcnt(6)
	v_mfma_f32_32x32x16_bf16 v[18:33], v[106:109], v[194:197], v[18:33]
	s_waitcnt lgkmcnt(5)
	v_mfma_f32_32x32x16_bf16 v[2:17], v[110:113], v[194:197], v[2:17]
	s_waitcnt lgkmcnt(0)
	v_max_f32_e32 v255, v255, v255
	v_max_f32_e32 v98, v254, v255
	v_add_u32_e32 v255, s6, v232
	v_add_u32_e32 v239, 0xc800, v255
	v_add_u32_e32 v255, 0xea00, v255
	s_cmp_lg_u32 s4, 34
	s_waitcnt vmcnt(0)
	ds_write2_b64 v239, v[178:179], v[180:181] offset1:1
	ds_write2_b64 v255, v[182:183], v[184:185] offset1:1
	s_waitcnt vmcnt(0)
	s_waitcnt lgkmcnt(0)
	s_barrier
	v_mfma_f32_32x32x16_bf16 v[50:65], v[114:117], v[198:201], v[50:65]
	v_mfma_f32_32x32x16_bf16 v[34:49], v[118:121], v[198:201], v[34:49]
	v_mfma_f32_32x32x16_bf16 v[18:33], v[122:125], v[198:201], v[18:33]
	v_mfma_f32_32x32x16_bf16 v[2:17], v[126:129], v[198:201], v[2:17]
	s_cbranch_scc0 .LBB0_1845
